# P5 out-projection: the four second-round 256x256 units are split 4-way along K over 16 workgroups (f32 partial slabs, fixed-order reduction), same bf16-MFMA f32-accumulate numerics
# baseline (speedup 1.0000x reference)
.LBB0_591:
	s_or_b64 exec, exec, s[0:1]
	s_mov_b32 s98, 0
	s_mov_b32 s99, 0
	s_mov_b32 s100, 0
	s_mov_b32 s101, 12
	s_cmpk_lt_i32 s88, 0x104
	s_cselect_b64 s[6:7], -1, 0
	v_mov_b32_e32 v8, v222
	s_waitcnt lgkmcnt(0)
	s_barrier
	s_and_b64 vcc, exec, s[6:7]
	v_readfirstlane_b32 s12, v8
	s_cbranch_vccz .LBB0_593
	v_readlane_b32 s2, v247, 18
	s_lshl_b32 s1, s2, 5
	s_or_b32 s1, s1, 4
	s_mul_i32 s0, s2, 33
	s_cmp_lt_i32 s2, 4
	s_cselect_b32 s0, s0, s1
	v_readlane_b32 s1, v247, 25
	s_add_i32 s0, s0, s1
	s_ashr_i32 s1, s0, 31
	s_lshr_b32 s1, s1, 27
	s_add_i32 s1, s0, s1
	s_ashr_i32 s2, s1, 5
	s_lshl_b32 s2, s2, 3
	s_sub_i32 s3, 0x41, s2
	s_min_u32 s3, s3, 8
	s_andn2_b32 s1, s1, 31
	s_sub_i32 s4, s0, s1
	v_cvt_f32_ubyte0_e32 v1, s3
	v_cvt_f32_i32_e32 v0, s4
	v_rcp_iflag_f32_e32 v2, v1
	s_ashr_i32 s0, s4, 30
	s_or_b32 s5, s0, 1
	v_mul_f32_e32 v2, v0, v2
	v_trunc_f32_e32 v2, v2
	v_fma_f32 v0, -v2, v1, v0
	v_cvt_i32_f32_e32 v2, v2
	v_cmp_ge_f32_e64 s[0:1], |v0|, v1
	s_and_b64 s[0:1], s[0:1], exec
	s_cselect_b32 s0, s5, 0
	v_readfirstlane_b32 s1, v2
	s_add_i32 s1, s1, s0
	s_sext_i32_i8 s0, s1
	s_mul_i32 s1, s1, s3
	s_sub_i32 s1, s4, s1
	s_sext_i32_i8 s1, s1
	s_add_i32 s2, s2, s1

.LBB0_598:
	s_mov_b32 s99, s98
	s_cmp_eq_u32 s99, 0
	s_cselect_b32 s101, 12, 0
	s_andn2_b64 vcc, exec, s[0:1]
	s_mov_b32 s0, s30
	s_mov_b32 s2, s36
	s_mov_b64 s[10:11], s[40:41]
	s_mov_b64 s[8:9], s[38:39]
	s_cbranch_vccz .LBB0_660
.LBB0_599:
	s_add_i32 s45, s45, 1
	s_mul_i32 s1, s45, s29
	s_mul_hi_u32 s6, s45, s28
	s_add_i32 s6, s6, s1
	s_mul_i32 s1, s45, s28
	s_add_u32 s12, s1, s88
	s_addc_u32 s13, s6, s89
	s_mov_b32 s98, 0
	s_mov_b32 s100, 0
	s_cmp_eq_u32 s45, 1
	s_cbranch_scc0 .Lks5_nosub
	s_cmp_lt_u32 s88, 16
	s_cbranch_scc0 .Lks5_nosub
	s_and_b32 s12, s88, 3
	s_add_i32 s12, s12, 0x100
	s_mov_b32 s13, 0
	s_lshr_b32 s100, s88, 2
	s_add_i32 s98, s100, 1
	s_lshl_b32 s100, s100, 9
.Lks5_nosub:
	v_cmp_gt_i64_e32 vcc, s[12:13], v[206:207]
	v_cmp_lt_i64_e64 s[6:7], s[12:13], v[204:205]
	s_cbranch_vccnz .LBB0_605
	s_ashr_i32 s1, s12, 31
	s_lshr_b32 s1, s1, 29
	s_add_i32 s1, s12, s1
	s_and_b32 s13, s1, -8
	s_sub_i32 s30, s12, s13
	s_cmp_gt_i32 s30, 3
	s_mov_b64 s[12:13], -1
	s_cbranch_scc0 .LBB0_602
	s_lshl_b32 s12, s30, 5
	s_or_b32 s31, s12, 4
	s_mov_b64 s[12:13], 0

.LBB0_605:
	s_ashr_i32 s37, s36, 31
	s_lshl_b64 s[12:13], s[36:37], 19
	s_add_u32 s38, s90, s12
	s_addc_u32 s39, s91, s13
	s_add_u32 s38, s38, s100
	s_addc_u32 s39, s39, 0
	s_and_b64 s[12:13], s[6:7], exec
	s_cselect_b32 s1, s39, s9
	s_cselect_b32 s37, s38, s8
	s_ashr_i32 s31, s30, 31
	s_lshl_b64 s[12:13], s[30:31], 19
	v_readlane_b32 s4, v247, 6
	v_readlane_b32 s5, v247, 7
	s_add_u32 s40, s4, s12
	s_addc_u32 s41, s5, s13
	s_add_u32 s40, s40, s100
	s_addc_u32 s41, s41, 0
	s_and_b64 s[12:13], s[6:7], exec
	s_cselect_b32 s31, s41, s11
	s_cselect_b32 s58, s40, s10
	s_add_u32 s8, s8, 0x40080
	s_addc_u32 s9, s9, 0
	s_add_u32 s59, s10, 0x100
	v_mov_b32_e32 v0, 0
	s_addc_u32 s60, s11, 0
	s_mov_b32 s61, -2
	s_waitcnt lgkmcnt(0)
	v_mov_b32_e32 v1, v0
	v_mov_b32_e32 v2, v0
	v_mov_b32_e32 v3, v0
	v_mov_b32_e32 v4, v0
	v_mov_b32_e32 v5, v0
	v_mov_b32_e32 v6, v0
	v_mov_b32_e32 v7, v0
	v_mov_b32_e32 v16, v0
	v_mov_b32_e32 v17, v0
	v_mov_b32_e32 v18, v0
	v_mov_b32_e32 v19, v0
	s_waitcnt vmcnt(0)
	v_mov_b32_e32 v20, v0
	v_mov_b32_e32 v21, v0
	v_mov_b32_e32 v22, v0
	v_mov_b32_e32 v23, v0
	v_mov_b32_e32 v32, v0
	v_mov_b32_e32 v33, v0
	v_mov_b32_e32 v34, v0
	v_mov_b32_e32 v35, v0
	v_mov_b32_e32 v36, v0
	v_mov_b32_e32 v37, v0
	v_mov_b32_e32 v38, v0
	v_mov_b32_e32 v39, v0
	v_mov_b32_e32 v48, v0
	v_mov_b32_e32 v49, v0
	v_mov_b32_e32 v50, v0
	v_mov_b32_e32 v51, v0
	v_mov_b32_e32 v52, v0
	v_mov_b32_e32 v53, v0
	v_mov_b32_e32 v54, v0
	v_mov_b32_e32 v55, v0
	v_mov_b32_e32 v8, v0
	v_mov_b32_e32 v9, v0
	v_mov_b32_e32 v10, v0
	v_mov_b32_e32 v11, v0
	v_mov_b32_e32 v12, v0
	v_mov_b32_e32 v13, v0
	v_mov_b32_e32 v14, v0
	v_mov_b32_e32 v15, v0
	v_mov_b32_e32 v24, v0
	v_mov_b32_e32 v25, v0
	v_mov_b32_e32 v26, v0
	v_mov_b32_e32 v27, v0
	v_mov_b32_e32 v28, v0
	v_mov_b32_e32 v29, v0
	v_mov_b32_e32 v30, v0
	v_mov_b32_e32 v31, v0
	v_mov_b32_e32 v40, v0
	v_mov_b32_e32 v41, v0
	v_mov_b32_e32 v42, v0
	v_mov_b32_e32 v43, v0
	v_mov_b32_e32 v44, v0
	v_mov_b32_e32 v45, v0
	v_mov_b32_e32 v46, v0
	v_mov_b32_e32 v47, v0
	v_mov_b32_e32 v56, v0
	v_mov_b32_e32 v57, v0
	v_mov_b32_e32 v58, v0
	v_mov_b32_e32 v59, v0
	v_mov_b32_e32 v60, v0
	v_mov_b32_e32 v61, v0
	v_mov_b32_e32 v62, v0
	v_mov_b32_e32 v63, v0
	v_mov_b32_e32 v64, v0
	v_mov_b32_e32 v65, v0
	v_mov_b32_e32 v66, v0
	v_mov_b32_e32 v67, v0
	v_mov_b32_e32 v68, v0
	v_mov_b32_e32 v69, v0
	v_mov_b32_e32 v70, v0
	v_mov_b32_e32 v71, v0
	v_mov_b32_e32 v80, v0
	v_mov_b32_e32 v81, v0
	v_mov_b32_e32 v82, v0
	v_mov_b32_e32 v83, v0
	v_mov_b32_e32 v84, v0
	v_mov_b32_e32 v85, v0
	v_mov_b32_e32 v86, v0
	v_mov_b32_e32 v87, v0
	v_mov_b32_e32 v96, v0
	v_mov_b32_e32 v97, v0
	v_mov_b32_e32 v98, v0
	v_mov_b32_e32 v99, v0
	v_mov_b32_e32 v100, v0
	v_mov_b32_e32 v101, v0
	v_mov_b32_e32 v102, v0
	v_mov_b32_e32 v103, v0
	v_mov_b32_e32 v112, v0
	v_mov_b32_e32 v113, v0
	v_mov_b32_e32 v114, v0
	v_mov_b32_e32 v115, v0
	v_mov_b32_e32 v116, v0
	v_mov_b32_e32 v117, v0
	v_mov_b32_e32 v118, v0
	v_mov_b32_e32 v119, v0
	v_mov_b32_e32 v72, v0
	v_mov_b32_e32 v73, v0
	v_mov_b32_e32 v74, v0
	v_mov_b32_e32 v75, v0
	v_mov_b32_e32 v76, v0
	v_mov_b32_e32 v77, v0
	v_mov_b32_e32 v78, v0
	v_mov_b32_e32 v79, v0
	v_mov_b32_e32 v88, v0
	v_mov_b32_e32 v89, v0
	v_mov_b32_e32 v90, v0
	v_mov_b32_e32 v91, v0
	v_mov_b32_e32 v92, v0
	v_mov_b32_e32 v93, v0
	v_mov_b32_e32 v94, v0
	v_mov_b32_e32 v95, v0
	v_mov_b32_e32 v104, v0
	v_mov_b32_e32 v105, v0
	v_mov_b32_e32 v106, v0
	v_mov_b32_e32 v107, v0
	v_mov_b32_e32 v108, v0
	v_mov_b32_e32 v109, v0
	v_mov_b32_e32 v110, v0
	v_mov_b32_e32 v111, v0
	v_mov_b32_e32 v120, v0
	v_mov_b32_e32 v121, v0
	v_mov_b32_e32 v122, v0
	v_mov_b32_e32 v123, v0
	v_mov_b32_e32 v124, v0
	v_mov_b32_e32 v125, v0
	v_mov_b32_e32 v126, v0
	v_mov_b32_e32 v127, v0
.LBB0_606:
	ds_read_b128 v[128:131], v227
	ds_read_b128 v[132:135], v227 offset:1024
	ds_read_b128 v[136:139], v227 offset:2048
	ds_read_b128 v[140:143], v227 offset:3072
	ds_read_b128 v[144:147], v228
	ds_read_b128 v[148:151], v228 offset:1024
	ds_read_b128 v[152:155], v228 offset:2048
	ds_read_b128 v[156:159], v228 offset:3072
	s_add_u32 s10, s8, 0xfffc0080
	s_addc_u32 s11, s9, -1
	s_cmp_eq_u32 s61, s101
	s_cselect_b32 s13, s1, s11
	s_cselect_b32 s12, s37, s10
	s_cselect_b32 s11, s31, s60
	s_cselect_b32 s10, s58, s59
	v_lshl_add_u64 v[208:209], s[8:9], 0, v[200:201]
	s_add_i32 m0, s3, 0xc000
	ds_read_b128 v[160:163], v229
	ds_read_b128 v[164:167], v229 offset:1024
	ds_read_b128 v[168:171], v229 offset:2048
	ds_read_b128 v[172:175], v229 offset:3072
	ds_read_b128 v[176:179], v229 offset:4096
	ds_read_b128 v[180:183], v229 offset:5120
	ds_read_b128 v[184:187], v229 offset:6144
	ds_read_b128 v[188:191], v229 offset:7168
	global_load_lds_dwordx4 v[208:209], off
	v_lshl_add_u64 v[208:209], s[8:9], 0, v[202:203]
	s_add_i32 m0, s3, 0xe000
	s_nop 0
	global_load_lds_dwordx4 v[208:209], off
	s_waitcnt vmcnt(8)
	s_waitcnt lgkmcnt(0)
	s_barrier
	s_setprio 1
	s_waitcnt lgkmcnt(0)
	v_mfma_f32_16x16x32_bf16 v[124:127], v[128:131], v[160:163], v[124:127]
	v_mfma_f32_16x16x32_bf16 v[120:123], v[136:139], v[160:163], v[120:123]
	v_mfma_f32_16x16x32_bf16 v[108:111], v[128:131], v[168:171], v[108:111]
	v_mfma_f32_16x16x32_bf16 v[104:107], v[136:139], v[168:171], v[104:107]
	v_mfma_f32_16x16x32_bf16 v[92:95], v[128:131], v[176:179], v[92:95]
	v_mfma_f32_16x16x32_bf16 v[88:91], v[136:139], v[176:179], v[88:91]
	v_mfma_f32_16x16x32_bf16 v[76:79], v[128:131], v[184:187], v[76:79]
	v_mfma_f32_16x16x32_bf16 v[72:75], v[136:139], v[184:187], v[72:75]
	v_mfma_f32_16x16x32_bf16 v[124:127], v[132:135], v[164:167], v[124:127]
	v_mfma_f32_16x16x32_bf16 v[120:123], v[140:143], v[164:167], v[120:123]
	v_mfma_f32_16x16x32_bf16 v[108:111], v[132:135], v[172:175], v[108:111]
	v_mfma_f32_16x16x32_bf16 v[104:107], v[140:143], v[172:175], v[104:107]
	v_mfma_f32_16x16x32_bf16 v[92:95], v[132:135], v[180:183], v[92:95]
	v_mfma_f32_16x16x32_bf16 v[88:91], v[140:143], v[180:183], v[88:91]
	v_mfma_f32_16x16x32_bf16 v[76:79], v[132:135], v[188:191], v[76:79]
	v_mfma_f32_16x16x32_bf16 v[72:75], v[140:143], v[188:191], v[72:75]
	s_setprio 0
	s_setprio 1
	v_mfma_f32_16x16x32_bf16 v[116:119], v[144:147], v[160:163], v[116:119]
	v_mfma_f32_16x16x32_bf16 v[112:115], v[152:155], v[160:163], v[112:115]
	v_mfma_f32_16x16x32_bf16 v[100:103], v[144:147], v[168:171], v[100:103]
	v_mfma_f32_16x16x32_bf16 v[96:99], v[152:155], v[168:171], v[96:99]
	v_mfma_f32_16x16x32_bf16 v[84:87], v[144:147], v[176:179], v[84:87]
	v_mfma_f32_16x16x32_bf16 v[80:83], v[152:155], v[176:179], v[80:83]
	v_mfma_f32_16x16x32_bf16 v[68:71], v[144:147], v[184:187], v[68:71]
	v_mfma_f32_16x16x32_bf16 v[64:67], v[152:155], v[184:187], v[64:67]
	v_mfma_f32_16x16x32_bf16 v[116:119], v[148:151], v[164:167], v[116:119]
	v_mfma_f32_16x16x32_bf16 v[112:115], v[156:159], v[164:167], v[112:115]
	v_mfma_f32_16x16x32_bf16 v[100:103], v[148:151], v[172:175], v[100:103]
	v_mfma_f32_16x16x32_bf16 v[96:99], v[156:159], v[172:175], v[96:99]
	v_mfma_f32_16x16x32_bf16 v[84:87], v[148:151], v[180:183], v[84:87]
	v_mfma_f32_16x16x32_bf16 v[80:83], v[156:159], v[180:183], v[80:83]
	v_mfma_f32_16x16x32_bf16 v[68:71], v[148:151], v[188:191], v[68:71]
	v_mfma_f32_16x16x32_bf16 v[64:67], v[156:159], v[188:191], v[64:67]
	s_setprio 0
	s_barrier
	s_add_i32 s62, s55, s33
	v_lshl_add_u64 v[208:209], s[10:11], 0, v[194:195]
	s_mov_b32 m0, s62
	ds_read_b128 v[160:163], v229 offset:16384
	ds_read_b128 v[164:167], v229 offset:17408
	ds_read_b128 v[168:171], v229 offset:18432
	ds_read_b128 v[172:175], v229 offset:19456
	ds_read_b128 v[176:179], v229 offset:20480
	ds_read_b128 v[180:183], v229 offset:21504
	ds_read_b128 v[184:187], v229 offset:22528
	ds_read_b128 v[188:191], v229 offset:23552
	global_load_lds_dwordx4 v[208:209], off
	s_add_i32 m0, s62, 0x2000
	s_add_u32 s62, s10, 0x40000
	v_lshl_add_u64 v[210:211], s[10:11], 0, v[198:199]
	s_addc_u32 s63, s11, 0
	s_add_i32 s64, s56, s33
	global_load_lds_dwordx4 v[210:211], off
	v_lshl_add_u64 v[212:213], s[62:63], 0, v[194:195]
	s_mov_b32 m0, s64
	v_lshl_add_u64 v[214:215], s[12:13], 0, v[196:197]
	global_load_lds_dwordx4 v[212:213], off
	v_lshl_add_u64 v[212:213], s[62:63], 0, v[198:199]
	s_add_i32 m0, s64, 0x2000
	s_nop 0
	global_load_lds_dwordx4 v[212:213], off
	v_lshl_add_u64 v[212:213], s[12:13], 0, v[192:193]
	s_mov_b32 m0, s3
	s_nop 0
	global_load_lds_dwordx4 v[212:213], off
	s_mov_b32 m0, s42
	s_nop 0
	global_load_lds_dwordx4 v[214:215], off
	s_waitcnt vmcnt(8)
	s_waitcnt lgkmcnt(0)
	s_barrier
	s_setprio 1
	s_waitcnt lgkmcnt(0)
	v_mfma_f32_16x16x32_bf16 v[60:63], v[128:131], v[160:163], v[60:63]
	v_mfma_f32_16x16x32_bf16 v[56:59], v[136:139], v[160:163], v[56:59]
	v_mfma_f32_16x16x32_bf16 v[44:47], v[128:131], v[168:171], v[44:47]
	v_mfma_f32_16x16x32_bf16 v[40:43], v[136:139], v[168:171], v[40:43]
	v_mfma_f32_16x16x32_bf16 v[28:31], v[128:131], v[176:179], v[28:31]
	v_mfma_f32_16x16x32_bf16 v[24:27], v[136:139], v[176:179], v[24:27]
	v_mfma_f32_16x16x32_bf16 v[12:15], v[128:131], v[184:187], v[12:15]
	v_mfma_f32_16x16x32_bf16 v[8:11], v[136:139], v[184:187], v[8:11]
	v_mfma_f32_16x16x32_bf16 v[60:63], v[132:135], v[164:167], v[60:63]
	v_mfma_f32_16x16x32_bf16 v[56:59], v[140:143], v[164:167], v[56:59]
	v_mfma_f32_16x16x32_bf16 v[44:47], v[132:135], v[172:175], v[44:47]
	v_mfma_f32_16x16x32_bf16 v[40:43], v[140:143], v[172:175], v[40:43]
	v_mfma_f32_16x16x32_bf16 v[28:31], v[132:135], v[180:183], v[28:31]
	v_mfma_f32_16x16x32_bf16 v[24:27], v[140:143], v[180:183], v[24:27]
	v_mfma_f32_16x16x32_bf16 v[12:15], v[132:135], v[188:191], v[12:15]
	v_mfma_f32_16x16x32_bf16 v[8:11], v[140:143], v[188:191], v[8:11]
	s_setprio 0
	s_setprio 1
	v_mfma_f32_16x16x32_bf16 v[52:55], v[144:147], v[160:163], v[52:55]
	v_mfma_f32_16x16x32_bf16 v[48:51], v[152:155], v[160:163], v[48:51]
	v_mfma_f32_16x16x32_bf16 v[36:39], v[144:147], v[168:171], v[36:39]
	v_mfma_f32_16x16x32_bf16 v[32:35], v[152:155], v[168:171], v[32:35]
	v_mfma_f32_16x16x32_bf16 v[20:23], v[144:147], v[176:179], v[20:23]
	v_mfma_f32_16x16x32_bf16 v[16:19], v[152:155], v[176:179], v[16:19]
	v_mfma_f32_16x16x32_bf16 v[4:7], v[144:147], v[184:187], v[4:7]
	v_mfma_f32_16x16x32_bf16 v[0:3], v[152:155], v[184:187], v[0:3]
	v_mfma_f32_16x16x32_bf16 v[52:55], v[148:151], v[164:167], v[52:55]
	v_mfma_f32_16x16x32_bf16 v[48:51], v[156:159], v[164:167], v[48:51]
	v_mfma_f32_16x16x32_bf16 v[36:39], v[148:151], v[172:175], v[36:39]
	v_mfma_f32_16x16x32_bf16 v[32:35], v[156:159], v[172:175], v[32:35]
	v_mfma_f32_16x16x32_bf16 v[20:23], v[148:151], v[180:183], v[20:23]
	v_mfma_f32_16x16x32_bf16 v[16:19], v[156:159], v[180:183], v[16:19]
	v_mfma_f32_16x16x32_bf16 v[4:7], v[148:151], v[188:191], v[4:7]
	v_mfma_f32_16x16x32_bf16 v[0:3], v[156:159], v[188:191], v[0:3]
	s_setprio 0
	s_barrier
	s_add_i32 s62, 0, 0x18000
	s_add_i32 s63, 0, 0x1c000
	v_add_u32_e32 v140, s62, v226
	v_add_u32_e32 v156, s63, v226
	ds_read_b128 v[128:131], v140
	ds_read_b128 v[132:135], v140 offset:1024
	ds_read_b128 v[136:139], v140 offset:2048
	ds_read_b128 v[140:143], v140 offset:3072
	ds_read_b128 v[144:147], v156
	ds_read_b128 v[148:151], v156 offset:1024
	ds_read_b128 v[152:155], v156 offset:2048
	ds_read_b128 v[156:159], v156 offset:3072
	s_add_u32 s12, s12, 0x40000
	s_addc_u32 s13, s13, 0
	s_mov_b32 m0, s43
	v_lshl_add_u64 v[216:217], s[12:13], 0, v[192:193]
	ds_read_b128 v[160:163], v229 offset:32768
	ds_read_b128 v[164:167], v229 offset:33792
	ds_read_b128 v[168:171], v229 offset:34816
	ds_read_b128 v[172:175], v229 offset:35840
	ds_read_b128 v[176:179], v229 offset:36864
	ds_read_b128 v[180:183], v229 offset:37888
	ds_read_b128 v[184:187], v229 offset:38912
	ds_read_b128 v[188:191], v229 offset:39936
	global_load_lds_dwordx4 v[216:217], off
	v_lshl_add_u64 v[216:217], s[12:13], 0, v[196:197]
	s_mov_b32 m0, s44
	s_nop 0
	global_load_lds_dwordx4 v[216:217], off
	s_waitcnt vmcnt(8)
	s_waitcnt lgkmcnt(0)
	s_barrier
	s_setprio 1
	s_waitcnt lgkmcnt(0)
	v_mfma_f32_16x16x32_bf16 v[124:127], v[128:131], v[160:163], v[124:127]
	v_mfma_f32_16x16x32_bf16 v[120:123], v[136:139], v[160:163], v[120:123]
	v_mfma_f32_16x16x32_bf16 v[108:111], v[128:131], v[168:171], v[108:111]
	v_mfma_f32_16x16x32_bf16 v[104:107], v[136:139], v[168:171], v[104:107]
	v_mfma_f32_16x16x32_bf16 v[92:95], v[128:131], v[176:179], v[92:95]
	v_mfma_f32_16x16x32_bf16 v[88:91], v[136:139], v[176:179], v[88:91]
	v_mfma_f32_16x16x32_bf16 v[76:79], v[128:131], v[184:187], v[76:79]
	v_mfma_f32_16x16x32_bf16 v[72:75], v[136:139], v[184:187], v[72:75]
	v_mfma_f32_16x16x32_bf16 v[124:127], v[132:135], v[164:167], v[124:127]
	v_mfma_f32_16x16x32_bf16 v[120:123], v[140:143], v[164:167], v[120:123]
	v_mfma_f32_16x16x32_bf16 v[108:111], v[132:135], v[172:175], v[108:111]
	v_mfma_f32_16x16x32_bf16 v[104:107], v[140:143], v[172:175], v[104:107]
	v_mfma_f32_16x16x32_bf16 v[92:95], v[132:135], v[180:183], v[92:95]
	v_mfma_f32_16x16x32_bf16 v[88:91], v[140:143], v[180:183], v[88:91]
	v_mfma_f32_16x16x32_bf16 v[76:79], v[132:135], v[188:191], v[76:79]
	v_mfma_f32_16x16x32_bf16 v[72:75], v[140:143], v[188:191], v[72:75]
	s_setprio 0
	s_setprio 1
	v_mfma_f32_16x16x32_bf16 v[116:119], v[144:147], v[160:163], v[116:119]
	v_mfma_f32_16x16x32_bf16 v[112:115], v[152:155], v[160:163], v[112:115]
	v_mfma_f32_16x16x32_bf16 v[100:103], v[144:147], v[168:171], v[100:103]
	v_mfma_f32_16x16x32_bf16 v[96:99], v[152:155], v[168:171], v[96:99]
	v_mfma_f32_16x16x32_bf16 v[84:87], v[144:147], v[176:179], v[84:87]
	v_mfma_f32_16x16x32_bf16 v[80:83], v[152:155], v[176:179], v[80:83]
	v_mfma_f32_16x16x32_bf16 v[68:71], v[144:147], v[184:187], v[68:71]
	v_mfma_f32_16x16x32_bf16 v[64:67], v[152:155], v[184:187], v[64:67]
	v_mfma_f32_16x16x32_bf16 v[116:119], v[148:151], v[164:167], v[116:119]
	v_mfma_f32_16x16x32_bf16 v[112:115], v[156:159], v[164:167], v[112:115]
	v_mfma_f32_16x16x32_bf16 v[100:103], v[148:151], v[172:175], v[100:103]
	v_mfma_f32_16x16x32_bf16 v[96:99], v[156:159], v[172:175], v[96:99]
	v_mfma_f32_16x16x32_bf16 v[84:87], v[148:151], v[180:183], v[84:87]
	v_mfma_f32_16x16x32_bf16 v[80:83], v[156:159], v[180:183], v[80:83]
	v_mfma_f32_16x16x32_bf16 v[68:71], v[148:151], v[188:191], v[68:71]
	v_mfma_f32_16x16x32_bf16 v[64:67], v[156:159], v[188:191], v[64:67]
	s_setprio 0
	s_barrier
	s_add_i32 s12, s62, s33
	v_lshl_add_u64 v[208:209], v[208:209], 0, s[16:17]
	s_mov_b32 m0, s12
	ds_read_b128 v[160:163], v229 offset:49152
	ds_read_b128 v[164:167], v229 offset:50176
	ds_read_b128 v[168:171], v229 offset:51200
	ds_read_b128 v[172:175], v229 offset:52224
	ds_read_b128 v[176:179], v229 offset:53248
	ds_read_b128 v[180:183], v229 offset:54272
	ds_read_b128 v[184:187], v229 offset:55296
	ds_read_b128 v[188:191], v229 offset:56320
	global_load_lds_dwordx4 v[208:209], off
	s_add_i32 m0, s12, 0x2000
	s_add_u32 s10, s10, 0x40080
	v_lshl_add_u64 v[208:209], v[210:211], 0, s[16:17]
	s_addc_u32 s11, s11, 0
	s_add_i32 s12, s63, s33
	global_load_lds_dwordx4 v[208:209], off
	v_lshl_add_u64 v[208:209], s[10:11], 0, v[194:195]
	s_mov_b32 m0, s12
	s_nop 0
	global_load_lds_dwordx4 v[208:209], off
	v_lshl_add_u64 v[208:209], s[10:11], 0, v[198:199]
	s_add_i32 m0, s12, 0x2000
	s_nop 0
	global_load_lds_dwordx4 v[208:209], off
	v_lshl_add_u64 v[208:209], v[212:213], 0, s[16:17]
	s_mov_b32 m0, s53
	s_nop 0
	global_load_lds_dwordx4 v[208:209], off
	v_lshl_add_u64 v[208:209], v[214:215], 0, s[16:17]
	s_mov_b32 m0, s54
	s_nop 0
	global_load_lds_dwordx4 v[208:209], off
	s_waitcnt vmcnt(8)
	s_waitcnt lgkmcnt(0)
	s_barrier
	s_setprio 1
	s_waitcnt lgkmcnt(0)
	v_mfma_f32_16x16x32_bf16 v[60:63], v[128:131], v[160:163], v[60:63]
	v_mfma_f32_16x16x32_bf16 v[56:59], v[136:139], v[160:163], v[56:59]
	v_mfma_f32_16x16x32_bf16 v[44:47], v[128:131], v[168:171], v[44:47]
	v_mfma_f32_16x16x32_bf16 v[40:43], v[136:139], v[168:171], v[40:43]
	v_mfma_f32_16x16x32_bf16 v[28:31], v[128:131], v[176:179], v[28:31]
	v_mfma_f32_16x16x32_bf16 v[24:27], v[136:139], v[176:179], v[24:27]
	v_mfma_f32_16x16x32_bf16 v[12:15], v[128:131], v[184:187], v[12:15]
	v_mfma_f32_16x16x32_bf16 v[8:11], v[136:139], v[184:187], v[8:11]
	v_mfma_f32_16x16x32_bf16 v[60:63], v[132:135], v[164:167], v[60:63]
	v_mfma_f32_16x16x32_bf16 v[56:59], v[140:143], v[164:167], v[56:59]
	v_mfma_f32_16x16x32_bf16 v[44:47], v[132:135], v[172:175], v[44:47]
	v_mfma_f32_16x16x32_bf16 v[40:43], v[140:143], v[172:175], v[40:43]
	v_mfma_f32_16x16x32_bf16 v[28:31], v[132:135], v[180:183], v[28:31]
	v_mfma_f32_16x16x32_bf16 v[24:27], v[140:143], v[180:183], v[24:27]
	v_mfma_f32_16x16x32_bf16 v[12:15], v[132:135], v[188:191], v[12:15]
	v_mfma_f32_16x16x32_bf16 v[8:11], v[140:143], v[188:191], v[8:11]
	s_setprio 0
	s_setprio 1
	v_mfma_f32_16x16x32_bf16 v[52:55], v[144:147], v[160:163], v[52:55]
	v_mfma_f32_16x16x32_bf16 v[48:51], v[152:155], v[160:163], v[48:51]
	v_mfma_f32_16x16x32_bf16 v[36:39], v[144:147], v[168:171], v[36:39]
	v_mfma_f32_16x16x32_bf16 v[32:35], v[152:155], v[168:171], v[32:35]
	v_mfma_f32_16x16x32_bf16 v[20:23], v[144:147], v[176:179], v[20:23]
	v_mfma_f32_16x16x32_bf16 v[16:19], v[152:155], v[176:179], v[16:19]
	v_mfma_f32_16x16x32_bf16 v[4:7], v[144:147], v[184:187], v[4:7]
	v_mfma_f32_16x16x32_bf16 v[0:3], v[152:155], v[184:187], v[0:3]
	v_mfma_f32_16x16x32_bf16 v[52:55], v[148:151], v[164:167], v[52:55]
	v_mfma_f32_16x16x32_bf16 v[48:51], v[156:159], v[164:167], v[48:51]
	v_mfma_f32_16x16x32_bf16 v[36:39], v[148:151], v[172:175], v[36:39]
	v_mfma_f32_16x16x32_bf16 v[32:35], v[156:159], v[172:175], v[32:35]
	v_mfma_f32_16x16x32_bf16 v[20:23], v[148:151], v[180:183], v[20:23]
	v_mfma_f32_16x16x32_bf16 v[16:19], v[156:159], v[180:183], v[16:19]
	v_mfma_f32_16x16x32_bf16 v[4:7], v[148:151], v[188:191], v[4:7]
	v_mfma_f32_16x16x32_bf16 v[0:3], v[156:159], v[188:191], v[0:3]
	s_setprio 0
	s_barrier
	s_add_i32 s61, s61, 2
	s_add_u32 s8, s8, 0x100
	s_addc_u32 s9, s9, 0
	s_add_u32 s59, s59, 0x100
	s_addc_u32 s60, s60, 0
	s_cmp_gt_u32 s61, s101
	s_cbranch_scc0 .LBB0_606
	s_and_b64 vcc, exec, s[18:19]
	s_cbranch_vccz .LBB0_609
	s_barrier
.LBB0_609:
	s_cmp_eq_u32 s99, 0
	s_cbranch_scc1 .Lks5_epi
	v_lshlrev_b32_e32 v160, 4, v222
	s_and_b32 s8, s88, 3
	s_lshl_b32 s8, s8, 6
	s_add_u32 s10, s24, s8
	s_addc_u32 s11, s25, 0
	s_add_u32 s10, s10, 0x1e03800
	s_addc_u32 s11, s11, 0
	s_cmp_eq_u32 s99, 1
	s_cbranch_scc1 .Lks5_reduce
	s_sub_i32 s8, s88, 4
	s_lshl_b32 s8, s8, 18
	s_add_u32 s4, s24, s8
	s_addc_u32 s5, s25, 0
	s_add_u32 s4, s4, 0x12200000
	s_addc_u32 s5, s5, 0
	global_store_dwordx4 v160, v[0:3], s[4:5]
	s_add_u32 s4, s4, 0x2000
	s_addc_u32 s5, s5, 0
	global_store_dwordx4 v160, v[4:7], s[4:5]
	s_add_u32 s4, s4, 0x2000
	s_addc_u32 s5, s5, 0
	global_store_dwordx4 v160, v[8:11], s[4:5]
	s_add_u32 s4, s4, 0x2000
	s_addc_u32 s5, s5, 0
	global_store_dwordx4 v160, v[12:15], s[4:5]
	s_add_u32 s4, s4, 0x2000
	s_addc_u32 s5, s5, 0
	global_store_dwordx4 v160, v[16:19], s[4:5]
	s_add_u32 s4, s4, 0x2000
	s_addc_u32 s5, s5, 0
	global_store_dwordx4 v160, v[20:23], s[4:5]
	s_add_u32 s4, s4, 0x2000
	s_addc_u32 s5, s5, 0
	global_store_dwordx4 v160, v[24:27], s[4:5]
	s_add_u32 s4, s4, 0x2000
	s_addc_u32 s5, s5, 0
	global_store_dwordx4 v160, v[28:31], s[4:5]
	s_add_u32 s4, s4, 0x2000
	s_addc_u32 s5, s5, 0
	global_store_dwordx4 v160, v[32:35], s[4:5]
	s_add_u32 s4, s4, 0x2000
	s_addc_u32 s5, s5, 0
	global_store_dwordx4 v160, v[36:39], s[4:5]
	s_add_u32 s4, s4, 0x2000
	s_addc_u32 s5, s5, 0
	global_store_dwordx4 v160, v[40:43], s[4:5]
	s_add_u32 s4, s4, 0x2000
	s_addc_u32 s5, s5, 0
	global_store_dwordx4 v160, v[44:47], s[4:5]
	s_add_u32 s4, s4, 0x2000
	s_addc_u32 s5, s5, 0
	global_store_dwordx4 v160, v[48:51], s[4:5]
	s_add_u32 s4, s4, 0x2000
	s_addc_u32 s5, s5, 0
	global_store_dwordx4 v160, v[52:55], s[4:5]
	s_add_u32 s4, s4, 0x2000
	s_addc_u32 s5, s5, 0
	global_store_dwordx4 v160, v[56:59], s[4:5]
	s_add_u32 s4, s4, 0x2000
	s_addc_u32 s5, s5, 0
	global_store_dwordx4 v160, v[60:63], s[4:5]
	s_add_u32 s4, s4, 0x2000
	s_addc_u32 s5, s5, 0
	global_store_dwordx4 v160, v[64:67], s[4:5]
	s_add_u32 s4, s4, 0x2000
	s_addc_u32 s5, s5, 0
	global_store_dwordx4 v160, v[68:71], s[4:5]
	s_add_u32 s4, s4, 0x2000
	s_addc_u32 s5, s5, 0
	global_store_dwordx4 v160, v[72:75], s[4:5]
	s_add_u32 s4, s4, 0x2000
	s_addc_u32 s5, s5, 0
	global_store_dwordx4 v160, v[76:79], s[4:5]
	s_add_u32 s4, s4, 0x2000
	s_addc_u32 s5, s5, 0
	global_store_dwordx4 v160, v[80:83], s[4:5]
	s_add_u32 s4, s4, 0x2000
	s_addc_u32 s5, s5, 0
	global_store_dwordx4 v160, v[84:87], s[4:5]
	s_add_u32 s4, s4, 0x2000
	s_addc_u32 s5, s5, 0
	global_store_dwordx4 v160, v[88:91], s[4:5]
	s_add_u32 s4, s4, 0x2000
	s_addc_u32 s5, s5, 0
	global_store_dwordx4 v160, v[92:95], s[4:5]
	s_add_u32 s4, s4, 0x2000
	s_addc_u32 s5, s5, 0
	global_store_dwordx4 v160, v[96:99], s[4:5]
	s_add_u32 s4, s4, 0x2000
	s_addc_u32 s5, s5, 0
	global_store_dwordx4 v160, v[100:103], s[4:5]
	s_add_u32 s4, s4, 0x2000
	s_addc_u32 s5, s5, 0
	global_store_dwordx4 v160, v[104:107], s[4:5]
	s_add_u32 s4, s4, 0x2000
	s_addc_u32 s5, s5, 0
	global_store_dwordx4 v160, v[108:111], s[4:5]
	s_add_u32 s4, s4, 0x2000
	s_addc_u32 s5, s5, 0
	global_store_dwordx4 v160, v[112:115], s[4:5]
	s_add_u32 s4, s4, 0x2000
	s_addc_u32 s5, s5, 0
	global_store_dwordx4 v160, v[116:119], s[4:5]
	s_add_u32 s4, s4, 0x2000
	s_addc_u32 s5, s5, 0
	global_store_dwordx4 v160, v[120:123], s[4:5]
	s_add_u32 s4, s4, 0x2000
	s_addc_u32 s5, s5, 0
	global_store_dwordx4 v160, v[124:127], s[4:5]
	s_add_u32 s4, s4, 0x2000
	s_addc_u32 s5, s5, 0
	s_waitcnt vmcnt(0)
	s_barrier
	v_cmp_eq_u32_e32 vcc, 0, v222
	s_and_saveexec_b64 s[12:13], vcc
	s_cbranch_execz .Lks5_nr_done
	buffer_wbl2 sc1
	s_waitcnt vmcnt(0)
	v_mov_b32_e32 v161, 0
	v_mov_b32_e32 v162, 1
	global_atomic_add v161, v162, s[10:11]
	s_waitcnt vmcnt(0)
.Lks5_nr_done:
	s_or_b64 exec, exec, s[12:13]
	s_mov_b64 s[0:1], -1
	s_branch .LBB0_598
.Lks5_reduce:
	v_cmp_eq_u32_e32 vcc, 0, v222
	s_and_saveexec_b64 s[12:13], vcc
	s_cbranch_execz .Lks5_wait_done
	v_mov_b32_e32 v161, 0
	s_mov_b32 s8, 0
.Lks5_spin:
	global_load_dword v162, v161, s[10:11] sc1
	s_waitcnt vmcnt(0)
	v_readfirstlane_b32 s9, v162
	s_cmp_ge_u32 s9, 3
	s_cbranch_scc1 .Lks5_spin_done
	s_sleep 1
	s_add_i32 s8, s8, 1
	s_cmp_lt_u32 s8, 0x5000
	s_cbranch_scc1 .Lks5_spin
.Lks5_spin_done:
	buffer_inv sc1
	s_waitcnt vmcnt(0)
.Lks5_wait_done:
	s_or_b64 exec, exec, s[12:13]
	s_barrier
	s_lshl_b32 s8, s88, 18
	s_add_u32 s4, s24, s8
	s_addc_u32 s5, s25, 0
	s_add_u32 s4, s4, 0x12200000
	s_addc_u32 s5, s5, 0
	global_load_dwordx4 v[128:131], v160, s[4:5]
	s_add_u32 s4, s4, 0x2000
	s_addc_u32 s5, s5, 0
	global_load_dwordx4 v[132:135], v160, s[4:5]
	s_add_u32 s4, s4, 0x2000
	s_addc_u32 s5, s5, 0
	global_load_dwordx4 v[136:139], v160, s[4:5]
	s_add_u32 s4, s4, 0x2000
	s_addc_u32 s5, s5, 0
	global_load_dwordx4 v[140:143], v160, s[4:5]
	s_add_u32 s4, s4, 0x2000
	s_addc_u32 s5, s5, 0
	global_load_dwordx4 v[144:147], v160, s[4:5]
	s_add_u32 s4, s4, 0x2000
	s_addc_u32 s5, s5, 0
	global_load_dwordx4 v[148:151], v160, s[4:5]
	s_add_u32 s4, s4, 0x2000
	s_addc_u32 s5, s5, 0
	global_load_dwordx4 v[152:155], v160, s[4:5]
	s_add_u32 s4, s4, 0x2000
	s_addc_u32 s5, s5, 0
	global_load_dwordx4 v[156:159], v160, s[4:5]
	s_add_u32 s4, s4, 0x2000
	s_addc_u32 s5, s5, 0
	s_waitcnt vmcnt(7)
	v_add_f32_e32 v0, v0, v128
	v_add_f32_e32 v1, v1, v129
	v_add_f32_e32 v2, v2, v130
	v_add_f32_e32 v3, v3, v131
	s_waitcnt vmcnt(6)
	v_add_f32_e32 v4, v4, v132
	v_add_f32_e32 v5, v5, v133
	v_add_f32_e32 v6, v6, v134
	v_add_f32_e32 v7, v7, v135
	s_waitcnt vmcnt(5)
	v_add_f32_e32 v8, v8, v136
	v_add_f32_e32 v9, v9, v137
	v_add_f32_e32 v10, v10, v138
	v_add_f32_e32 v11, v11, v139
	s_waitcnt vmcnt(4)
	v_add_f32_e32 v12, v12, v140
	v_add_f32_e32 v13, v13, v141
	v_add_f32_e32 v14, v14, v142
	v_add_f32_e32 v15, v15, v143
	s_waitcnt vmcnt(3)
	v_add_f32_e32 v16, v16, v144
	v_add_f32_e32 v17, v17, v145
	v_add_f32_e32 v18, v18, v146
	v_add_f32_e32 v19, v19, v147
	s_waitcnt vmcnt(2)
	v_add_f32_e32 v20, v20, v148
	v_add_f32_e32 v21, v21, v149
	v_add_f32_e32 v22, v22, v150
	v_add_f32_e32 v23, v23, v151
	s_waitcnt vmcnt(1)
	v_add_f32_e32 v24, v24, v152
	v_add_f32_e32 v25, v25, v153
	v_add_f32_e32 v26, v26, v154
	v_add_f32_e32 v27, v27, v155
	s_waitcnt vmcnt(0)
	v_add_f32_e32 v28, v28, v156
	v_add_f32_e32 v29, v29, v157
	v_add_f32_e32 v30, v30, v158
	v_add_f32_e32 v31, v31, v159
	global_load_dwordx4 v[128:131], v160, s[4:5]
	s_add_u32 s4, s4, 0x2000
	s_addc_u32 s5, s5, 0
	global_load_dwordx4 v[132:135], v160, s[4:5]
	s_add_u32 s4, s4, 0x2000
	s_addc_u32 s5, s5, 0
	global_load_dwordx4 v[136:139], v160, s[4:5]
	s_add_u32 s4, s4, 0x2000
	s_addc_u32 s5, s5, 0
	global_load_dwordx4 v[140:143], v160, s[4:5]
	s_add_u32 s4, s4, 0x2000
	s_addc_u32 s5, s5, 0
	global_load_dwordx4 v[144:147], v160, s[4:5]
	s_add_u32 s4, s4, 0x2000
	s_addc_u32 s5, s5, 0
	global_load_dwordx4 v[148:151], v160, s[4:5]
	s_add_u32 s4, s4, 0x2000
	s_addc_u32 s5, s5, 0
	global_load_dwordx4 v[152:155], v160, s[4:5]
	s_add_u32 s4, s4, 0x2000
	s_addc_u32 s5, s5, 0
	global_load_dwordx4 v[156:159], v160, s[4:5]
	s_add_u32 s4, s4, 0x2000
	s_addc_u32 s5, s5, 0
	s_waitcnt vmcnt(7)
	v_add_f32_e32 v32, v32, v128
	v_add_f32_e32 v33, v33, v129
	v_add_f32_e32 v34, v34, v130
	v_add_f32_e32 v35, v35, v131
	s_waitcnt vmcnt(6)
	v_add_f32_e32 v36, v36, v132
	v_add_f32_e32 v37, v37, v133
	v_add_f32_e32 v38, v38, v134
	v_add_f32_e32 v39, v39, v135
	s_waitcnt vmcnt(5)
	v_add_f32_e32 v40, v40, v136
	v_add_f32_e32 v41, v41, v137
	v_add_f32_e32 v42, v42, v138
	v_add_f32_e32 v43, v43, v139
	s_waitcnt vmcnt(4)
	v_add_f32_e32 v44, v44, v140
	v_add_f32_e32 v45, v45, v141
	v_add_f32_e32 v46, v46, v142
	v_add_f32_e32 v47, v47, v143
	s_waitcnt vmcnt(3)
	v_add_f32_e32 v48, v48, v144
	v_add_f32_e32 v49, v49, v145
	v_add_f32_e32 v50, v50, v146
	v_add_f32_e32 v51, v51, v147
	s_waitcnt vmcnt(2)
	v_add_f32_e32 v52, v52, v148
	v_add_f32_e32 v53, v53, v149
	v_add_f32_e32 v54, v54, v150
	v_add_f32_e32 v55, v55, v151
	s_waitcnt vmcnt(1)
	v_add_f32_e32 v56, v56, v152
	v_add_f32_e32 v57, v57, v153
	v_add_f32_e32 v58, v58, v154
	v_add_f32_e32 v59, v59, v155
	s_waitcnt vmcnt(0)
	v_add_f32_e32 v60, v60, v156
	v_add_f32_e32 v61, v61, v157
	v_add_f32_e32 v62, v62, v158
	v_add_f32_e32 v63, v63, v159
	global_load_dwordx4 v[128:131], v160, s[4:5]
	s_add_u32 s4, s4, 0x2000
	s_addc_u32 s5, s5, 0
	global_load_dwordx4 v[132:135], v160, s[4:5]
	s_add_u32 s4, s4, 0x2000
	s_addc_u32 s5, s5, 0
	global_load_dwordx4 v[136:139], v160, s[4:5]
	s_add_u32 s4, s4, 0x2000
	s_addc_u32 s5, s5, 0
	global_load_dwordx4 v[140:143], v160, s[4:5]
	s_add_u32 s4, s4, 0x2000
	s_addc_u32 s5, s5, 0
	global_load_dwordx4 v[144:147], v160, s[4:5]
	s_add_u32 s4, s4, 0x2000
	s_addc_u32 s5, s5, 0
	global_load_dwordx4 v[148:151], v160, s[4:5]
	s_add_u32 s4, s4, 0x2000
	s_addc_u32 s5, s5, 0
	global_load_dwordx4 v[152:155], v160, s[4:5]
	s_add_u32 s4, s4, 0x2000
	s_addc_u32 s5, s5, 0
	global_load_dwordx4 v[156:159], v160, s[4:5]
	s_add_u32 s4, s4, 0x2000
	s_addc_u32 s5, s5, 0
	s_waitcnt vmcnt(7)
	v_add_f32_e32 v64, v64, v128
	v_add_f32_e32 v65, v65, v129
	v_add_f32_e32 v66, v66, v130
	v_add_f32_e32 v67, v67, v131
	s_waitcnt vmcnt(6)
	v_add_f32_e32 v68, v68, v132
	v_add_f32_e32 v69, v69, v133
	v_add_f32_e32 v70, v70, v134
	v_add_f32_e32 v71, v71, v135
	s_waitcnt vmcnt(5)
	v_add_f32_e32 v72, v72, v136
	v_add_f32_e32 v73, v73, v137
	v_add_f32_e32 v74, v74, v138
	v_add_f32_e32 v75, v75, v139
	s_waitcnt vmcnt(4)
	v_add_f32_e32 v76, v76, v140
	v_add_f32_e32 v77, v77, v141
	v_add_f32_e32 v78, v78, v142
	v_add_f32_e32 v79, v79, v143
	s_waitcnt vmcnt(3)
	v_add_f32_e32 v80, v80, v144
	v_add_f32_e32 v81, v81, v145
	v_add_f32_e32 v82, v82, v146
	v_add_f32_e32 v83, v83, v147
	s_waitcnt vmcnt(2)
	v_add_f32_e32 v84, v84, v148
	v_add_f32_e32 v85, v85, v149
	v_add_f32_e32 v86, v86, v150
	v_add_f32_e32 v87, v87, v151
	s_waitcnt vmcnt(1)
	v_add_f32_e32 v88, v88, v152
	v_add_f32_e32 v89, v89, v153
	v_add_f32_e32 v90, v90, v154
	v_add_f32_e32 v91, v91, v155
	s_waitcnt vmcnt(0)
	v_add_f32_e32 v92, v92, v156
	v_add_f32_e32 v93, v93, v157
	v_add_f32_e32 v94, v94, v158
	v_add_f32_e32 v95, v95, v159
	global_load_dwordx4 v[128:131], v160, s[4:5]
	s_add_u32 s4, s4, 0x2000
	s_addc_u32 s5, s5, 0
	global_load_dwordx4 v[132:135], v160, s[4:5]
	s_add_u32 s4, s4, 0x2000
	s_addc_u32 s5, s5, 0
	global_load_dwordx4 v[136:139], v160, s[4:5]
	s_add_u32 s4, s4, 0x2000
	s_addc_u32 s5, s5, 0
	global_load_dwordx4 v[140:143], v160, s[4:5]
	s_add_u32 s4, s4, 0x2000
	s_addc_u32 s5, s5, 0
	global_load_dwordx4 v[144:147], v160, s[4:5]
	s_add_u32 s4, s4, 0x2000
	s_addc_u32 s5, s5, 0
	global_load_dwordx4 v[148:151], v160, s[4:5]
	s_add_u32 s4, s4, 0x2000
	s_addc_u32 s5, s5, 0
	global_load_dwordx4 v[152:155], v160, s[4:5]
	s_add_u32 s4, s4, 0x2000
	s_addc_u32 s5, s5, 0
	global_load_dwordx4 v[156:159], v160, s[4:5]
	s_add_u32 s4, s4, 0x2000
	s_addc_u32 s5, s5, 0
	s_waitcnt vmcnt(7)
	v_add_f32_e32 v96, v96, v128
	v_add_f32_e32 v97, v97, v129
	v_add_f32_e32 v98, v98, v130
	v_add_f32_e32 v99, v99, v131
	s_waitcnt vmcnt(6)
	v_add_f32_e32 v100, v100, v132
	v_add_f32_e32 v101, v101, v133
	v_add_f32_e32 v102, v102, v134
	v_add_f32_e32 v103, v103, v135
	s_waitcnt vmcnt(5)
	v_add_f32_e32 v104, v104, v136
	v_add_f32_e32 v105, v105, v137
	v_add_f32_e32 v106, v106, v138
	v_add_f32_e32 v107, v107, v139
	s_waitcnt vmcnt(4)
	v_add_f32_e32 v108, v108, v140
	v_add_f32_e32 v109, v109, v141
	v_add_f32_e32 v110, v110, v142
	v_add_f32_e32 v111, v111, v143
	s_waitcnt vmcnt(3)
	v_add_f32_e32 v112, v112, v144
	v_add_f32_e32 v113, v113, v145
	v_add_f32_e32 v114, v114, v146
	v_add_f32_e32 v115, v115, v147
	s_waitcnt vmcnt(2)
	v_add_f32_e32 v116, v116, v148
	v_add_f32_e32 v117, v117, v149
	v_add_f32_e32 v118, v118, v150
	v_add_f32_e32 v119, v119, v151
	s_waitcnt vmcnt(1)
	v_add_f32_e32 v120, v120, v152
	v_add_f32_e32 v121, v121, v153
	v_add_f32_e32 v122, v122, v154
	v_add_f32_e32 v123, v123, v155
	s_waitcnt vmcnt(0)
	v_add_f32_e32 v124, v124, v156
	v_add_f32_e32 v125, v125, v157
	v_add_f32_e32 v126, v126, v158
	v_add_f32_e32 v127, v127, v159
	s_add_u32 s4, s4, 0xc0000
	s_addc_u32 s5, s5, 0
	global_load_dwordx4 v[128:131], v160, s[4:5]
	s_add_u32 s4, s4, 0x2000
	s_addc_u32 s5, s5, 0
	global_load_dwordx4 v[132:135], v160, s[4:5]
	s_add_u32 s4, s4, 0x2000
	s_addc_u32 s5, s5, 0
	global_load_dwordx4 v[136:139], v160, s[4:5]
	s_add_u32 s4, s4, 0x2000
	s_addc_u32 s5, s5, 0
	global_load_dwordx4 v[140:143], v160, s[4:5]
	s_add_u32 s4, s4, 0x2000
	s_addc_u32 s5, s5, 0
	global_load_dwordx4 v[144:147], v160, s[4:5]
	s_add_u32 s4, s4, 0x2000
	s_addc_u32 s5, s5, 0
	global_load_dwordx4 v[148:151], v160, s[4:5]
	s_add_u32 s4, s4, 0x2000
	s_addc_u32 s5, s5, 0
	global_load_dwordx4 v[152:155], v160, s[4:5]
	s_add_u32 s4, s4, 0x2000
	s_addc_u32 s5, s5, 0
	global_load_dwordx4 v[156:159], v160, s[4:5]
	s_add_u32 s4, s4, 0x2000
	s_addc_u32 s5, s5, 0
	s_waitcnt vmcnt(7)
	v_add_f32_e32 v0, v0, v128
	v_add_f32_e32 v1, v1, v129
	v_add_f32_e32 v2, v2, v130
	v_add_f32_e32 v3, v3, v131
	s_waitcnt vmcnt(6)
	v_add_f32_e32 v4, v4, v132
	v_add_f32_e32 v5, v5, v133
	v_add_f32_e32 v6, v6, v134
	v_add_f32_e32 v7, v7, v135
	s_waitcnt vmcnt(5)
	v_add_f32_e32 v8, v8, v136
	v_add_f32_e32 v9, v9, v137
	v_add_f32_e32 v10, v10, v138
	v_add_f32_e32 v11, v11, v139
	s_waitcnt vmcnt(4)
	v_add_f32_e32 v12, v12, v140
	v_add_f32_e32 v13, v13, v141
	v_add_f32_e32 v14, v14, v142
	v_add_f32_e32 v15, v15, v143
	s_waitcnt vmcnt(3)
	v_add_f32_e32 v16, v16, v144
	v_add_f32_e32 v17, v17, v145
	v_add_f32_e32 v18, v18, v146
	v_add_f32_e32 v19, v19, v147
	s_waitcnt vmcnt(2)
	v_add_f32_e32 v20, v20, v148
	v_add_f32_e32 v21, v21, v149
	v_add_f32_e32 v22, v22, v150
	v_add_f32_e32 v23, v23, v151
	s_waitcnt vmcnt(1)
	v_add_f32_e32 v24, v24, v152
	v_add_f32_e32 v25, v25, v153
	v_add_f32_e32 v26, v26, v154
	v_add_f32_e32 v27, v27, v155
	s_waitcnt vmcnt(0)
	v_add_f32_e32 v28, v28, v156
	v_add_f32_e32 v29, v29, v157
	v_add_f32_e32 v30, v30, v158
	v_add_f32_e32 v31, v31, v159
	global_load_dwordx4 v[128:131], v160, s[4:5]
	s_add_u32 s4, s4, 0x2000
	s_addc_u32 s5, s5, 0
	global_load_dwordx4 v[132:135], v160, s[4:5]
	s_add_u32 s4, s4, 0x2000
	s_addc_u32 s5, s5, 0
	global_load_dwordx4 v[136:139], v160, s[4:5]
	s_add_u32 s4, s4, 0x2000
	s_addc_u32 s5, s5, 0
	global_load_dwordx4 v[140:143], v160, s[4:5]
	s_add_u32 s4, s4, 0x2000
	s_addc_u32 s5, s5, 0
	global_load_dwordx4 v[144:147], v160, s[4:5]
	s_add_u32 s4, s4, 0x2000
	s_addc_u32 s5, s5, 0
	global_load_dwordx4 v[148:151], v160, s[4:5]
	s_add_u32 s4, s4, 0x2000
	s_addc_u32 s5, s5, 0
	global_load_dwordx4 v[152:155], v160, s[4:5]
	s_add_u32 s4, s4, 0x2000
	s_addc_u32 s5, s5, 0
	global_load_dwordx4 v[156:159], v160, s[4:5]
	s_add_u32 s4, s4, 0x2000
	s_addc_u32 s5, s5, 0
	s_waitcnt vmcnt(7)
	v_add_f32_e32 v32, v32, v128
	v_add_f32_e32 v33, v33, v129
	v_add_f32_e32 v34, v34, v130
	v_add_f32_e32 v35, v35, v131
	s_waitcnt vmcnt(6)
	v_add_f32_e32 v36, v36, v132
	v_add_f32_e32 v37, v37, v133
	v_add_f32_e32 v38, v38, v134
	v_add_f32_e32 v39, v39, v135
	s_waitcnt vmcnt(5)
	v_add_f32_e32 v40, v40, v136
	v_add_f32_e32 v41, v41, v137
	v_add_f32_e32 v42, v42, v138
	v_add_f32_e32 v43, v43, v139
	s_waitcnt vmcnt(4)
	v_add_f32_e32 v44, v44, v140
	v_add_f32_e32 v45, v45, v141
	v_add_f32_e32 v46, v46, v142
	v_add_f32_e32 v47, v47, v143
	s_waitcnt vmcnt(3)
	v_add_f32_e32 v48, v48, v144
	v_add_f32_e32 v49, v49, v145
	v_add_f32_e32 v50, v50, v146
	v_add_f32_e32 v51, v51, v147
	s_waitcnt vmcnt(2)
	v_add_f32_e32 v52, v52, v148
	v_add_f32_e32 v53, v53, v149
	v_add_f32_e32 v54, v54, v150
	v_add_f32_e32 v55, v55, v151
	s_waitcnt vmcnt(1)
	v_add_f32_e32 v56, v56, v152
	v_add_f32_e32 v57, v57, v153
	v_add_f32_e32 v58, v58, v154
	v_add_f32_e32 v59, v59, v155
	s_waitcnt vmcnt(0)
	v_add_f32_e32 v60, v60, v156
	v_add_f32_e32 v61, v61, v157
	v_add_f32_e32 v62, v62, v158
	v_add_f32_e32 v63, v63, v159
	global_load_dwordx4 v[128:131], v160, s[4:5]
	s_add_u32 s4, s4, 0x2000
	s_addc_u32 s5, s5, 0
	global_load_dwordx4 v[132:135], v160, s[4:5]
	s_add_u32 s4, s4, 0x2000
	s_addc_u32 s5, s5, 0
	global_load_dwordx4 v[136:139], v160, s[4:5]
	s_add_u32 s4, s4, 0x2000
	s_addc_u32 s5, s5, 0
	global_load_dwordx4 v[140:143], v160, s[4:5]
	s_add_u32 s4, s4, 0x2000
	s_addc_u32 s5, s5, 0
	global_load_dwordx4 v[144:147], v160, s[4:5]
	s_add_u32 s4, s4, 0x2000
	s_addc_u32 s5, s5, 0
	global_load_dwordx4 v[148:151], v160, s[4:5]
	s_add_u32 s4, s4, 0x2000
	s_addc_u32 s5, s5, 0
	global_load_dwordx4 v[152:155], v160, s[4:5]
	s_add_u32 s4, s4, 0x2000
	s_addc_u32 s5, s5, 0
	global_load_dwordx4 v[156:159], v160, s[4:5]
	s_add_u32 s4, s4, 0x2000
	s_addc_u32 s5, s5, 0
	s_waitcnt vmcnt(7)
	v_add_f32_e32 v64, v64, v128
	v_add_f32_e32 v65, v65, v129
	v_add_f32_e32 v66, v66, v130
	v_add_f32_e32 v67, v67, v131
	s_waitcnt vmcnt(6)
	v_add_f32_e32 v68, v68, v132
	v_add_f32_e32 v69, v69, v133
	v_add_f32_e32 v70, v70, v134
	v_add_f32_e32 v71, v71, v135
	s_waitcnt vmcnt(5)
	v_add_f32_e32 v72, v72, v136
	v_add_f32_e32 v73, v73, v137
	v_add_f32_e32 v74, v74, v138
	v_add_f32_e32 v75, v75, v139
	s_waitcnt vmcnt(4)
	v_add_f32_e32 v76, v76, v140
	v_add_f32_e32 v77, v77, v141
	v_add_f32_e32 v78, v78, v142
	v_add_f32_e32 v79, v79, v143
	s_waitcnt vmcnt(3)
	v_add_f32_e32 v80, v80, v144
	v_add_f32_e32 v81, v81, v145
	v_add_f32_e32 v82, v82, v146
	v_add_f32_e32 v83, v83, v147
	s_waitcnt vmcnt(2)
	v_add_f32_e32 v84, v84, v148
	v_add_f32_e32 v85, v85, v149
	v_add_f32_e32 v86, v86, v150
	v_add_f32_e32 v87, v87, v151
	s_waitcnt vmcnt(1)
	v_add_f32_e32 v88, v88, v152
	v_add_f32_e32 v89, v89, v153
	v_add_f32_e32 v90, v90, v154
	v_add_f32_e32 v91, v91, v155
	s_waitcnt vmcnt(0)
	v_add_f32_e32 v92, v92, v156
	v_add_f32_e32 v93, v93, v157
	v_add_f32_e32 v94, v94, v158
	v_add_f32_e32 v95, v95, v159
	global_load_dwordx4 v[128:131], v160, s[4:5]
	s_add_u32 s4, s4, 0x2000
	s_addc_u32 s5, s5, 0
	global_load_dwordx4 v[132:135], v160, s[4:5]
	s_add_u32 s4, s4, 0x2000
	s_addc_u32 s5, s5, 0
	global_load_dwordx4 v[136:139], v160, s[4:5]
	s_add_u32 s4, s4, 0x2000
	s_addc_u32 s5, s5, 0
	global_load_dwordx4 v[140:143], v160, s[4:5]
	s_add_u32 s4, s4, 0x2000
	s_addc_u32 s5, s5, 0
	global_load_dwordx4 v[144:147], v160, s[4:5]
	s_add_u32 s4, s4, 0x2000
	s_addc_u32 s5, s5, 0
	global_load_dwordx4 v[148:151], v160, s[4:5]
	s_add_u32 s4, s4, 0x2000
	s_addc_u32 s5, s5, 0
	global_load_dwordx4 v[152:155], v160, s[4:5]
	s_add_u32 s4, s4, 0x2000
	s_addc_u32 s5, s5, 0
	global_load_dwordx4 v[156:159], v160, s[4:5]
	s_add_u32 s4, s4, 0x2000
	s_addc_u32 s5, s5, 0
	s_waitcnt vmcnt(7)
	v_add_f32_e32 v96, v96, v128
	v_add_f32_e32 v97, v97, v129
	v_add_f32_e32 v98, v98, v130
	v_add_f32_e32 v99, v99, v131
	s_waitcnt vmcnt(6)
	v_add_f32_e32 v100, v100, v132
	v_add_f32_e32 v101, v101, v133
	v_add_f32_e32 v102, v102, v134
	v_add_f32_e32 v103, v103, v135
	s_waitcnt vmcnt(5)
	v_add_f32_e32 v104, v104, v136
	v_add_f32_e32 v105, v105, v137
	v_add_f32_e32 v106, v106, v138
	v_add_f32_e32 v107, v107, v139
	s_waitcnt vmcnt(4)
	v_add_f32_e32 v108, v108, v140
	v_add_f32_e32 v109, v109, v141
	v_add_f32_e32 v110, v110, v142
	v_add_f32_e32 v111, v111, v143
	s_waitcnt vmcnt(3)
	v_add_f32_e32 v112, v112, v144
	v_add_f32_e32 v113, v113, v145
	v_add_f32_e32 v114, v114, v146
	v_add_f32_e32 v115, v115, v147
	s_waitcnt vmcnt(2)
	v_add_f32_e32 v116, v116, v148
	v_add_f32_e32 v117, v117, v149
	v_add_f32_e32 v118, v118, v150
	v_add_f32_e32 v119, v119, v151
	s_waitcnt vmcnt(1)
	v_add_f32_e32 v120, v120, v152
	v_add_f32_e32 v121, v121, v153
	v_add_f32_e32 v122, v122, v154
	v_add_f32_e32 v123, v123, v155
	s_waitcnt vmcnt(0)
	v_add_f32_e32 v124, v124, v156
	v_add_f32_e32 v125, v125, v157
	v_add_f32_e32 v126, v126, v158
	v_add_f32_e32 v127, v127, v159
	s_add_u32 s4, s4, 0xc0000
	s_addc_u32 s5, s5, 0
	global_load_dwordx4 v[128:131], v160, s[4:5]
	s_add_u32 s4, s4, 0x2000
	s_addc_u32 s5, s5, 0
	global_load_dwordx4 v[132:135], v160, s[4:5]
	s_add_u32 s4, s4, 0x2000
	s_addc_u32 s5, s5, 0
	global_load_dwordx4 v[136:139], v160, s[4:5]
	s_add_u32 s4, s4, 0x2000
	s_addc_u32 s5, s5, 0
	global_load_dwordx4 v[140:143], v160, s[4:5]
	s_add_u32 s4, s4, 0x2000
	s_addc_u32 s5, s5, 0
	global_load_dwordx4 v[144:147], v160, s[4:5]
	s_add_u32 s4, s4, 0x2000
	s_addc_u32 s5, s5, 0
	global_load_dwordx4 v[148:151], v160, s[4:5]
	s_add_u32 s4, s4, 0x2000
	s_addc_u32 s5, s5, 0
	global_load_dwordx4 v[152:155], v160, s[4:5]
	s_add_u32 s4, s4, 0x2000
	s_addc_u32 s5, s5, 0
	global_load_dwordx4 v[156:159], v160, s[4:5]
	s_add_u32 s4, s4, 0x2000
	s_addc_u32 s5, s5, 0
	s_waitcnt vmcnt(7)
	v_add_f32_e32 v0, v0, v128
	v_add_f32_e32 v1, v1, v129
	v_add_f32_e32 v2, v2, v130
	v_add_f32_e32 v3, v3, v131
	s_waitcnt vmcnt(6)
	v_add_f32_e32 v4, v4, v132
	v_add_f32_e32 v5, v5, v133
	v_add_f32_e32 v6, v6, v134
	v_add_f32_e32 v7, v7, v135
	s_waitcnt vmcnt(5)
	v_add_f32_e32 v8, v8, v136
	v_add_f32_e32 v9, v9, v137
	v_add_f32_e32 v10, v10, v138
	v_add_f32_e32 v11, v11, v139
	s_waitcnt vmcnt(4)
	v_add_f32_e32 v12, v12, v140
	v_add_f32_e32 v13, v13, v141
	v_add_f32_e32 v14, v14, v142
	v_add_f32_e32 v15, v15, v143
	s_waitcnt vmcnt(3)
	v_add_f32_e32 v16, v16, v144
	v_add_f32_e32 v17, v17, v145
	v_add_f32_e32 v18, v18, v146
	v_add_f32_e32 v19, v19, v147
	s_waitcnt vmcnt(2)
	v_add_f32_e32 v20, v20, v148
	v_add_f32_e32 v21, v21, v149
	v_add_f32_e32 v22, v22, v150
	v_add_f32_e32 v23, v23, v151
	s_waitcnt vmcnt(1)
	v_add_f32_e32 v24, v24, v152
	v_add_f32_e32 v25, v25, v153
	v_add_f32_e32 v26, v26, v154
	v_add_f32_e32 v27, v27, v155
	s_waitcnt vmcnt(0)
	v_add_f32_e32 v28, v28, v156
	v_add_f32_e32 v29, v29, v157
	v_add_f32_e32 v30, v30, v158
	v_add_f32_e32 v31, v31, v159
	global_load_dwordx4 v[128:131], v160, s[4:5]
	s_add_u32 s4, s4, 0x2000
	s_addc_u32 s5, s5, 0
	global_load_dwordx4 v[132:135], v160, s[4:5]
	s_add_u32 s4, s4, 0x2000
	s_addc_u32 s5, s5, 0
	global_load_dwordx4 v[136:139], v160, s[4:5]
	s_add_u32 s4, s4, 0x2000
	s_addc_u32 s5, s5, 0
	global_load_dwordx4 v[140:143], v160, s[4:5]
	s_add_u32 s4, s4, 0x2000
	s_addc_u32 s5, s5, 0
	global_load_dwordx4 v[144:147], v160, s[4:5]
	s_add_u32 s4, s4, 0x2000
	s_addc_u32 s5, s5, 0
	global_load_dwordx4 v[148:151], v160, s[4:5]
	s_add_u32 s4, s4, 0x2000
	s_addc_u32 s5, s5, 0
	global_load_dwordx4 v[152:155], v160, s[4:5]
	s_add_u32 s4, s4, 0x2000
	s_addc_u32 s5, s5, 0
	global_load_dwordx4 v[156:159], v160, s[4:5]
	s_add_u32 s4, s4, 0x2000
	s_addc_u32 s5, s5, 0
	s_waitcnt vmcnt(7)
	v_add_f32_e32 v32, v32, v128
	v_add_f32_e32 v33, v33, v129
	v_add_f32_e32 v34, v34, v130
	v_add_f32_e32 v35, v35, v131
	s_waitcnt vmcnt(6)
	v_add_f32_e32 v36, v36, v132
	v_add_f32_e32 v37, v37, v133
	v_add_f32_e32 v38, v38, v134
	v_add_f32_e32 v39, v39, v135
	s_waitcnt vmcnt(5)
	v_add_f32_e32 v40, v40, v136
	v_add_f32_e32 v41, v41, v137
	v_add_f32_e32 v42, v42, v138
	v_add_f32_e32 v43, v43, v139
	s_waitcnt vmcnt(4)
	v_add_f32_e32 v44, v44, v140
	v_add_f32_e32 v45, v45, v141
	v_add_f32_e32 v46, v46, v142
	v_add_f32_e32 v47, v47, v143
	s_waitcnt vmcnt(3)
	v_add_f32_e32 v48, v48, v144
	v_add_f32_e32 v49, v49, v145
	v_add_f32_e32 v50, v50, v146
	v_add_f32_e32 v51, v51, v147
	s_waitcnt vmcnt(2)
	v_add_f32_e32 v52, v52, v148
	v_add_f32_e32 v53, v53, v149
	v_add_f32_e32 v54, v54, v150
	v_add_f32_e32 v55, v55, v151
	s_waitcnt vmcnt(1)
	v_add_f32_e32 v56, v56, v152
	v_add_f32_e32 v57, v57, v153
	v_add_f32_e32 v58, v58, v154
	v_add_f32_e32 v59, v59, v155
	s_waitcnt vmcnt(0)
	v_add_f32_e32 v60, v60, v156
	v_add_f32_e32 v61, v61, v157
	v_add_f32_e32 v62, v62, v158
	v_add_f32_e32 v63, v63, v159
	global_load_dwordx4 v[128:131], v160, s[4:5]
	s_add_u32 s4, s4, 0x2000
	s_addc_u32 s5, s5, 0
	global_load_dwordx4 v[132:135], v160, s[4:5]
	s_add_u32 s4, s4, 0x2000
	s_addc_u32 s5, s5, 0
	global_load_dwordx4 v[136:139], v160, s[4:5]
	s_add_u32 s4, s4, 0x2000
	s_addc_u32 s5, s5, 0
	global_load_dwordx4 v[140:143], v160, s[4:5]
	s_add_u32 s4, s4, 0x2000
	s_addc_u32 s5, s5, 0
	global_load_dwordx4 v[144:147], v160, s[4:5]
	s_add_u32 s4, s4, 0x2000
	s_addc_u32 s5, s5, 0
	global_load_dwordx4 v[148:151], v160, s[4:5]
	s_add_u32 s4, s4, 0x2000
	s_addc_u32 s5, s5, 0
	global_load_dwordx4 v[152:155], v160, s[4:5]
	s_add_u32 s4, s4, 0x2000
	s_addc_u32 s5, s5, 0
	global_load_dwordx4 v[156:159], v160, s[4:5]
	s_add_u32 s4, s4, 0x2000
	s_addc_u32 s5, s5, 0
	s_waitcnt vmcnt(7)
	v_add_f32_e32 v64, v64, v128
	v_add_f32_e32 v65, v65, v129
	v_add_f32_e32 v66, v66, v130
	v_add_f32_e32 v67, v67, v131
	s_waitcnt vmcnt(6)
	v_add_f32_e32 v68, v68, v132
	v_add_f32_e32 v69, v69, v133
	v_add_f32_e32 v70, v70, v134
	v_add_f32_e32 v71, v71, v135
	s_waitcnt vmcnt(5)
	v_add_f32_e32 v72, v72, v136
	v_add_f32_e32 v73, v73, v137
	v_add_f32_e32 v74, v74, v138
	v_add_f32_e32 v75, v75, v139
	s_waitcnt vmcnt(4)
	v_add_f32_e32 v76, v76, v140
	v_add_f32_e32 v77, v77, v141
	v_add_f32_e32 v78, v78, v142
	v_add_f32_e32 v79, v79, v143
	s_waitcnt vmcnt(3)
	v_add_f32_e32 v80, v80, v144
	v_add_f32_e32 v81, v81, v145
	v_add_f32_e32 v82, v82, v146
	v_add_f32_e32 v83, v83, v147
	s_waitcnt vmcnt(2)
	v_add_f32_e32 v84, v84, v148
	v_add_f32_e32 v85, v85, v149
	v_add_f32_e32 v86, v86, v150
	v_add_f32_e32 v87, v87, v151
	s_waitcnt vmcnt(1)
	v_add_f32_e32 v88, v88, v152
	v_add_f32_e32 v89, v89, v153
	v_add_f32_e32 v90, v90, v154
	v_add_f32_e32 v91, v91, v155
	s_waitcnt vmcnt(0)
	v_add_f32_e32 v92, v92, v156
	v_add_f32_e32 v93, v93, v157
	v_add_f32_e32 v94, v94, v158
	v_add_f32_e32 v95, v95, v159
	global_load_dwordx4 v[128:131], v160, s[4:5]
	s_add_u32 s4, s4, 0x2000
	s_addc_u32 s5, s5, 0
	global_load_dwordx4 v[132:135], v160, s[4:5]
	s_add_u32 s4, s4, 0x2000
	s_addc_u32 s5, s5, 0
	global_load_dwordx4 v[136:139], v160, s[4:5]
	s_add_u32 s4, s4, 0x2000
	s_addc_u32 s5, s5, 0
	global_load_dwordx4 v[140:143], v160, s[4:5]
	s_add_u32 s4, s4, 0x2000
	s_addc_u32 s5, s5, 0
	global_load_dwordx4 v[144:147], v160, s[4:5]
	s_add_u32 s4, s4, 0x2000
	s_addc_u32 s5, s5, 0
	global_load_dwordx4 v[148:151], v160, s[4:5]
	s_add_u32 s4, s4, 0x2000
	s_addc_u32 s5, s5, 0
	global_load_dwordx4 v[152:155], v160, s[4:5]
	s_add_u32 s4, s4, 0x2000
	s_addc_u32 s5, s5, 0
	global_load_dwordx4 v[156:159], v160, s[4:5]
	s_add_u32 s4, s4, 0x2000
	s_addc_u32 s5, s5, 0
	s_waitcnt vmcnt(7)
	v_add_f32_e32 v96, v96, v128
	v_add_f32_e32 v97, v97, v129
	v_add_f32_e32 v98, v98, v130
	v_add_f32_e32 v99, v99, v131
	s_waitcnt vmcnt(6)
	v_add_f32_e32 v100, v100, v132
	v_add_f32_e32 v101, v101, v133
	v_add_f32_e32 v102, v102, v134
	v_add_f32_e32 v103, v103, v135
	s_waitcnt vmcnt(5)
	v_add_f32_e32 v104, v104, v136
	v_add_f32_e32 v105, v105, v137
	v_add_f32_e32 v106, v106, v138
	v_add_f32_e32 v107, v107, v139
	s_waitcnt vmcnt(4)
	v_add_f32_e32 v108, v108, v140
	v_add_f32_e32 v109, v109, v141
	v_add_f32_e32 v110, v110, v142
	v_add_f32_e32 v111, v111, v143
	s_waitcnt vmcnt(3)
	v_add_f32_e32 v112, v112, v144
	v_add_f32_e32 v113, v113, v145
	v_add_f32_e32 v114, v114, v146
	v_add_f32_e32 v115, v115, v147
	s_waitcnt vmcnt(2)
	v_add_f32_e32 v116, v116, v148
	v_add_f32_e32 v117, v117, v149
	v_add_f32_e32 v118, v118, v150
	v_add_f32_e32 v119, v119, v151
	s_waitcnt vmcnt(1)
	v_add_f32_e32 v120, v120, v152
	v_add_f32_e32 v121, v121, v153
	v_add_f32_e32 v122, v122, v154
	v_add_f32_e32 v123, v123, v155
	s_waitcnt vmcnt(0)
	v_add_f32_e32 v124, v124, v156
	v_add_f32_e32 v125, v125, v157
	v_add_f32_e32 v126, v126, v158
	v_add_f32_e32 v127, v127, v159
	s_add_u32 s4, s4, 0xc0000
	s_addc_u32 s5, s5, 0

	.amdhsa_kernel _Z3fwd4Args
		.amdhsa_group_segment_fixed_size 0
		.amdhsa_private_segment_fixed_size 0
		.amdhsa_kernarg_size 408
		.amdhsa_user_sgpr_count 2
		.amdhsa_user_sgpr_dispatch_ptr 0
		.amdhsa_user_sgpr_queue_ptr 0
		.amdhsa_user_sgpr_kernarg_segment_ptr 1
		.amdhsa_user_sgpr_dispatch_id 0
		.amdhsa_user_sgpr_kernarg_preload_length 0
		.amdhsa_user_sgpr_kernarg_preload_offset 0
		.amdhsa_user_sgpr_private_segment_size 0
		.amdhsa_uses_dynamic_stack 0
		.amdhsa_enable_private_segment 0
		.amdhsa_system_sgpr_workgroup_id_x 1
		.amdhsa_system_sgpr_workgroup_id_y 0
		.amdhsa_system_sgpr_workgroup_id_z 0
		.amdhsa_system_sgpr_workgroup_info 0
		.amdhsa_system_vgpr_workitem_id 2
		.amdhsa_next_free_vgpr 256
		.amdhsa_next_free_sgpr 102
		.amdhsa_accum_offset 256
		.amdhsa_reserve_vcc 1
		.amdhsa_float_round_mode_32 0
		.amdhsa_float_round_mode_16_64 0
		.amdhsa_float_denorm_mode_32 3
		.amdhsa_float_denorm_mode_16_64 3
		.amdhsa_dx10_clamp 1
		.amdhsa_ieee_mode 1
		.amdhsa_fp16_overflow 0
		.amdhsa_tg_split 0
		.amdhsa_exception_fp_ieee_invalid_op 0
		.amdhsa_exception_fp_denorm_src 0
		.amdhsa_exception_fp_ieee_div_zero 0
		.amdhsa_exception_fp_ieee_overflow 0
		.amdhsa_exception_fp_ieee_underflow 0
		.amdhsa_exception_fp_ieee_inexact 0
		.amdhsa_exception_int_div_zero 0
	.end_amdhsa_kernel

amdhsa.kernels:
  - .agpr_count:     0
    .args:
      - .offset:         0
        .size:           152
        .value_kind:     by_value
      - .offset:         152
        .size:           4
        .value_kind:     hidden_block_count_x
      - .offset:         156
        .size:           4
        .value_kind:     hidden_block_count_y
      - .offset:         160
        .size:           4
        .value_kind:     hidden_block_count_z
      - .offset:         164
        .size:           2
        .value_kind:     hidden_group_size_x
      - .offset:         166
        .size:           2
        .value_kind:     hidden_group_size_y
      - .offset:         168
        .size:           2
        .value_kind:     hidden_group_size_z
      - .offset:         170
        .size:           2
        .value_kind:     hidden_remainder_x
      - .offset:         172
        .size:           2
        .value_kind:     hidden_remainder_y
      - .offset:         174
        .size:           2
        .value_kind:     hidden_remainder_z
      - .offset:         192
        .size:           8
        .value_kind:     hidden_global_offset_x
      - .offset:         200
        .size:           8
        .value_kind:     hidden_global_offset_y
      - .offset:         208
        .size:           8
        .value_kind:     hidden_global_offset_z
      - .offset:         216
        .size:           2
        .value_kind:     hidden_grid_dims
      - .offset:         240
        .size:           8
        .value_kind:     hidden_multigrid_sync_arg
      - .offset:         272
        .size:           4
        .value_kind:     hidden_dynamic_lds_size
    .group_segment_fixed_size: 0
    .kernarg_segment_align: 8
    .kernarg_segment_size: 408
    .language:       OpenCL C
    .language_version:
      - 2
      - 0
    .max_flat_workgroup_size: 512
    .name:           _Z3fwd4Args
    .private_segment_fixed_size: 0
    .sgpr_count:     108
    .sgpr_spill_count: 52
    .symbol:         _Z3fwd4Args.kd
    .uniform_work_group_size: 1
    .uses_dynamic_stack: false
    .vgpr_count:     256
    .vgpr_spill_count: 0
    .wavefront_size: 64
